# layer-0 norm through the hand-written row loop (reads x/ctx, seeds the residual stream); attention-phase third-round items moved to less loaded workgroups
# baseline (speedup 1.0000x reference)
.LBB0_159:
	v_mov_b32_e32 v0, v188
	v_readlane_b32 s0, v253, 49
	v_ashrrev_i32_e32 v2, 6, v0
	s_mul_i32 s25, s58, 9
	v_add_u32_e32 v18, s0, v2
	s_movk_i32 s0, 0x4800
	v_cmp_gt_i32_e32 vcc, s0, v18
	s_and_saveexec_b64 s[34:35], vcc
	v_writelane_b32 v253, s58, 19
	s_cbranch_execz .LBB0_172
	s_cmp_eq_u32 s58, 0
	s_cselect_b64 s[36:37], -1, 0
	s_cmp_lg_u32 s58, 0
	v_readlane_b32 s0, v253, 19
	v_cmp_lt_i32_e32 vcc, v193, v192
	s_cselect_b64 s[38:39], -1, 0
	s_lshl_b32 s60, s0, 10
	v_readlane_b32 s40, v252, 18
	v_cndmask_b32_e32 v3, v191, v193, vcc
	v_cmp_lt_i32_e32 vcc, v194, v192
	s_lshl_b64 s[0:1], s[60:61], 2
	v_readlane_b32 s52, v252, 30
	v_lshlrev_b32_e32 v34, 2, v3
	v_cndmask_b32_e32 v3, v191, v194, vcc
	v_cmp_lt_i32_e32 vcc, v195, v192
	v_readlane_b32 s53, v252, 31
	s_add_u32 s0, s52, s0
	v_and_b32_e32 v2, 63, v0
	v_lshlrev_b32_e32 v35, 2, v3
	v_cndmask_b32_e32 v3, v191, v195, vcc
	v_cmp_lt_i32_e32 vcc, v196, v192
	s_addc_u32 s1, s53, s1
	v_lshlrev_b32_e32 v0, 4, v2
	v_lshlrev_b32_e32 v36, 2, v3
	v_cndmask_b32_e32 v3, v191, v196, vcc
	v_cmp_lt_i32_e32 vcc, v197, v192
	v_readlane_b32 s48, v252, 26
	v_readlane_b32 s49, v252, 27
	v_readlane_b32 s50, v252, 28
	v_readlane_b32 s51, v252, 29
	v_lshlrev_b32_e32 v4, 2, v2
	v_lshl_add_u64 v[20:21], s[0:1], 0, v[0:1]
	v_lshlrev_b32_e32 v37, 2, v3
	v_cndmask_b32_e32 v3, v191, v197, vcc
	v_cmp_lt_i32_e32 vcc, v198, v192
	v_readlane_b32 s0, v253, 40
	v_readlane_b32 s41, v252, 19
	v_readlane_b32 s48, v252, 14
	v_readlane_b32 s50, v251, 2
	v_readlane_b32 s22, v253, 47
	v_lshlrev_b32_e32 v38, 2, v3
	v_cndmask_b32_e32 v3, v191, v198, vcc
	v_or_b32_e32 v6, 0x100, v4
	v_or_b32_e32 v8, 0x200, v4
	v_or_b32_e32 v10, 0x300, v4
	v_lshl_add_u64 v[22:23], s[94:95], 0, v[0:1]
	v_lshlrev_b32_e32 v0, 3, v2
	v_readlane_b32 s1, v253, 41
	v_readlane_b32 s58, v253, 19
	s_mov_b32 s19, 0x800000
	v_readlane_b32 s49, v252, 15
	v_readlane_b32 s51, v251, 3
	v_readlane_b32 s23, v253, 48
	v_lshlrev_b32_e32 v39, 2, v3
	v_lshl_add_u64 v[24:25], s[0:1], 0, v[0:1]
	s_mov_b64 s[40:41], 0
	v_lshlrev_b32_e32 v0, 4, v2
	v_lshlrev_b32_e32 v26, 2, v4
	v_lshlrev_b32_e32 v28, 2, v6
	v_lshlrev_b32_e32 v30, 2, v8
	v_lshlrev_b32_e32 v32, 2, v10
	v_readlane_b32 s42, v252, 20
	v_readlane_b32 s43, v252, 21
	v_readlane_b32 s44, v252, 22
	v_readlane_b32 s45, v252, 23
	v_readlane_b32 s46, v252, 24
	v_readlane_b32 s47, v252, 25
	v_readlane_b32 s54, v252, 32
	v_readlane_b32 s55, v252, 33
	s_cmp_lg_u32 s58, 0
	s_cbranch_scc0 .Lnseed
	v_and_b32_e32 v96, 63, v188
	v_lshlrev_b32_e32 v2, 4, v96
	v_lshlrev_b32_e32 v3, 3, v96
	v_lshlrev_b32_e32 v100, 2, v96
	v_xor_b32_e32 v4, 0x80, v100
	v_xor_b32_e32 v5, 0x40, v100
	v_xor_b32_e32 v6, 0x20, v100
	v_xor_b32_e32 v7, 0x10, v100
	v_xor_b32_e32 v8, 0x8, v100
	v_xor_b32_e32 v9, 0x4, v100
	v_readfirstlane_b32 s98, v18
	v_mov_b32_e32 v110, v24
	v_mov_b32_e32 v111, v25
	s_movk_i32 s99, 0x4800
	s_mul_i32 s0, s25, 0x6000
	s_add_u32 s100, s22, s0
	s_addc_u32 s101, s23, 0
	v_readfirstlane_b32 s0, v20
	v_readfirstlane_b32 s1, v21
	s_nop 4
	global_load_dwordx4 v[48:51], v2, s[0:1]
	global_load_dwordx4 v[52:55], v2, s[0:1] offset:1024
	global_load_dwordx4 v[56:59], v2, s[0:1] offset:2048
	global_load_dwordx4 v[60:63], v2, s[0:1] offset:3072
	s_lshl_b32 s0, s98, 12
	s_add_u32 s0, s94, s0
	s_addc_u32 s1, s95, 0
	global_load_dwordx4 v[32:35], v2, s[0:1]
	global_load_dwordx4 v[36:39], v2, s[0:1] offset:1024
	global_load_dwordx4 v[40:43], v2, s[0:1] offset:2048
	global_load_dwordx4 v[44:47], v2, s[0:1] offset:3072
	s_waitcnt vmcnt(0)
	s_branch .Lnbody_0

.Lnbody_0:
	v_mov_b32_e32 v16, v32
	v_mov_b32_e32 v17, v33
	v_mov_b32_e32 v18, v34
	v_mov_b32_e32 v19, v35
	v_mov_b32_e32 v20, v36
	v_mov_b32_e32 v21, v37
	v_mov_b32_e32 v22, v38
	v_mov_b32_e32 v23, v39
	v_mov_b32_e32 v24, v40
	v_mov_b32_e32 v25, v41
	v_mov_b32_e32 v26, v42
	v_mov_b32_e32 v27, v43
	v_mov_b32_e32 v28, v44
	v_mov_b32_e32 v29, v45
	v_mov_b32_e32 v30, v46
	v_mov_b32_e32 v31, v47
	s_min_u32 s0, s98, 0x4000
	s_lshr_b32 s0, s0, 11
	s_mul_i32 s0, s0, 0x6000
	s_add_u32 s2, s100, s0
	s_addc_u32 s3, s101, 0
	global_load_dwordx4 v[80:83], v2, s[2:3]
	global_load_dwordx4 v[84:87], v2, s[2:3] offset:1024
	global_load_dwordx4 v[88:91], v2, s[2:3] offset:2048
	global_load_dwordx4 v[92:95], v2, s[2:3] offset:3072
	s_add_u32 s0, s2, 0x1000
	s_addc_u32 s1, s3, 0
	global_load_dwordx4 v[64:67], v2, s[0:1]
	global_load_dwordx4 v[68:71], v2, s[0:1] offset:1024
	global_load_dwordx4 v[72:75], v2, s[0:1] offset:2048
	global_load_dwordx4 v[76:79], v2, s[0:1] offset:3072
	s_add_u32 s2, s98, s91
	s_cmp_lt_u32 s2, s99
	s_cselect_b32 s3, s2, s98
	s_lshl_b32 s0, s3, 12
	s_add_u32 s0, s94, s0
	s_addc_u32 s1, s95, 0
	global_load_dwordx4 v[32:35], v2, s[0:1]
	global_load_dwordx4 v[36:39], v2, s[0:1] offset:1024
	global_load_dwordx4 v[40:43], v2, s[0:1] offset:2048
	global_load_dwordx4 v[44:47], v2, s[0:1] offset:3072
	v_mul_f32_e32 v97, v16, v16
	v_mul_f32_e32 v98, v20, v20
	v_mul_f32_e32 v99, v24, v24
	v_mul_f32_e32 v100, v28, v28
	v_fmac_f32_e32 v97, v17, v17
	v_fmac_f32_e32 v98, v21, v21
	v_fmac_f32_e32 v99, v25, v25
	v_fmac_f32_e32 v100, v29, v29
	v_fmac_f32_e32 v97, v18, v18
	v_fmac_f32_e32 v98, v22, v22
	v_fmac_f32_e32 v99, v26, v26
	v_fmac_f32_e32 v100, v30, v30
	v_fmac_f32_e32 v97, v19, v19
	v_fmac_f32_e32 v98, v23, v23
	v_fmac_f32_e32 v99, v27, v27
	v_fmac_f32_e32 v100, v31, v31
	v_add_f32_e32 v97, v97, v98
	v_add_f32_e32 v99, v99, v100
	v_add_f32_e32 v96, v97, v99
	ds_bpermute_b32 v97, v4, v96
	s_waitcnt lgkmcnt(0)
	v_add_f32_e32 v96, v96, v97
	ds_bpermute_b32 v97, v5, v96
	s_waitcnt lgkmcnt(0)
	v_add_f32_e32 v96, v96, v97
	ds_bpermute_b32 v97, v6, v96
	s_waitcnt lgkmcnt(0)
	v_add_f32_e32 v96, v96, v97
	ds_bpermute_b32 v97, v7, v96
	s_waitcnt lgkmcnt(0)
	v_add_f32_e32 v96, v96, v97
	ds_bpermute_b32 v97, v8, v96
	s_waitcnt lgkmcnt(0)
	v_add_f32_e32 v96, v96, v97
	ds_bpermute_b32 v97, v9, v96
	s_waitcnt lgkmcnt(0)
	v_add_f32_e32 v96, v96, v97
	v_fmamk_f32 v96, v96, 0x3a800000, v189
	v_rsq_f32_e32 v96, v96
	v_readfirstlane_b32 s0, v110
	v_readfirstlane_b32 s1, v111
	s_lshl_b32 s3, s98, 11
	s_add_u32 s0, s0, s3
	s_addc_u32 s1, s1, 0
	s_waitcnt vmcnt(4)
	v_mul_f32_e32 v16, v16, v96
	v_mul_f32_e32 v17, v17, v96
	v_mul_f32_e32 v18, v18, v96
	v_mul_f32_e32 v19, v19, v96
	v_mul_f32_e32 v20, v20, v96
	v_mul_f32_e32 v21, v21, v96
	v_mul_f32_e32 v22, v22, v96
	v_mul_f32_e32 v23, v23, v96
	v_mul_f32_e32 v24, v24, v96
	v_mul_f32_e32 v25, v25, v96
	v_mul_f32_e32 v26, v26, v96
	v_mul_f32_e32 v27, v27, v96
	v_mul_f32_e32 v28, v28, v96
	v_mul_f32_e32 v29, v29, v96
	v_mul_f32_e32 v30, v30, v96
	v_mul_f32_e32 v31, v31, v96
	v_mul_f32_e32 v16, v16, v48
	v_mul_f32_e32 v17, v17, v49
	v_mul_f32_e32 v18, v18, v50
	v_mul_f32_e32 v19, v19, v51
	v_mul_f32_e32 v20, v20, v52
	v_mul_f32_e32 v21, v21, v53
	v_mul_f32_e32 v22, v22, v54
	v_mul_f32_e32 v23, v23, v55
	v_mul_f32_e32 v24, v24, v56
	v_mul_f32_e32 v25, v25, v57
	v_mul_f32_e32 v26, v26, v58
	v_mul_f32_e32 v27, v27, v59
	v_mul_f32_e32 v28, v28, v60
	v_mul_f32_e32 v29, v29, v61
	v_mul_f32_e32 v30, v30, v62
	v_mul_f32_e32 v31, v31, v63
	v_add_f32_e32 v64, 1.0, v64
	v_add_f32_e32 v65, 1.0, v65
	v_add_f32_e32 v66, 1.0, v66
	v_add_f32_e32 v67, 1.0, v67
	v_add_f32_e32 v68, 1.0, v68
	v_add_f32_e32 v69, 1.0, v69
	v_add_f32_e32 v70, 1.0, v70
	v_add_f32_e32 v71, 1.0, v71
	v_add_f32_e32 v72, 1.0, v72
	v_add_f32_e32 v73, 1.0, v73
	v_add_f32_e32 v74, 1.0, v74
	v_add_f32_e32 v75, 1.0, v75
	v_add_f32_e32 v76, 1.0, v76
	v_add_f32_e32 v77, 1.0, v77
	v_add_f32_e32 v78, 1.0, v78
	v_add_f32_e32 v79, 1.0, v79
	v_fma_f32 v16, v16, v64, v80
	v_fma_f32 v17, v17, v65, v81
	v_fma_f32 v18, v18, v66, v82
	v_fma_f32 v19, v19, v67, v83
	v_fma_f32 v20, v20, v68, v84
	v_fma_f32 v21, v21, v69, v85
	v_fma_f32 v22, v22, v70, v86
	v_fma_f32 v23, v23, v71, v87
	v_fma_f32 v24, v24, v72, v88
	v_fma_f32 v25, v25, v73, v89
	v_fma_f32 v26, v26, v74, v90
	v_fma_f32 v27, v27, v75, v91
	v_fma_f32 v28, v28, v76, v92
	v_fma_f32 v29, v29, v77, v93
	v_fma_f32 v30, v30, v78, v94
	v_fma_f32 v31, v31, v79, v95
	v_cvt_pk_bf16_f32 v102, v16, v17
	v_cvt_pk_bf16_f32 v103, v18, v19
	v_cvt_pk_bf16_f32 v104, v20, v21
	v_cvt_pk_bf16_f32 v105, v22, v23
	v_cvt_pk_bf16_f32 v106, v24, v25
	v_cvt_pk_bf16_f32 v107, v26, v27
	v_cvt_pk_bf16_f32 v108, v28, v29
	v_cvt_pk_bf16_f32 v109, v30, v31
	global_store_dwordx2 v3, v[102:103], s[0:1]
	global_store_dwordx2 v3, v[104:105], s[0:1] offset:512
	global_store_dwordx2 v3, v[106:107], s[0:1] offset:1024
	global_store_dwordx2 v3, v[108:109], s[0:1] offset:1536
	s_mov_b32 s98, s2
	s_cmp_lt_u32 s98, s99
	s_cbranch_scc1 .Lntop_0
	s_branch .LBB0_172
.Lnseed:
	v_and_b32_e32 v96, 63, v188
	v_lshlrev_b32_e32 v2, 4, v96
	v_lshlrev_b32_e32 v3, 3, v96
	v_lshlrev_b32_e32 v100, 2, v96
	v_xor_b32_e32 v4, 0x80, v100
	v_xor_b32_e32 v5, 0x40, v100
	v_xor_b32_e32 v6, 0x20, v100
	v_xor_b32_e32 v7, 0x10, v100
	v_xor_b32_e32 v8, 0x8, v100
	v_xor_b32_e32 v9, 0x4, v100
	v_readfirstlane_b32 s98, v18
	v_mov_b32_e32 v110, v24
	v_mov_b32_e32 v111, v25
	s_movk_i32 s99, 0x4800
	s_mul_i32 s0, s25, 0x6000
	s_add_u32 s100, s22, s0
	s_addc_u32 s101, s23, 0
	v_readfirstlane_b32 s0, v20
	v_readfirstlane_b32 s1, v21
	s_nop 4
	global_load_dwordx4 v[48:51], v2, s[0:1]
	global_load_dwordx4 v[52:55], v2, s[0:1] offset:1024
	global_load_dwordx4 v[56:59], v2, s[0:1] offset:2048
	global_load_dwordx4 v[60:63], v2, s[0:1] offset:3072
	s_cmp_lt_u32 s98, 0x4000
	s_cbranch_scc0 .Lnctx_f2
	v_readlane_b32 s0, v252, 18
	v_readlane_b32 s1, v252, 19
	s_lshl_b32 s3, s98, 12
	s_branch .Lnjoin_f2
.Lnctx_f2:
	v_readlane_b32 s0, v252, 22
	v_readlane_b32 s1, v252, 23
	s_sub_u32 s3, s98, 0x4000
	s_lshl_b32 s3, s3, 12
.Lnjoin_f2:
	s_nop 1
	s_add_u32 s0, s0, s3
	s_addc_u32 s1, s1, 0
	global_load_dwordx4 v[32:35], v2, s[0:1]
	global_load_dwordx4 v[36:39], v2, s[0:1] offset:1024
	global_load_dwordx4 v[40:43], v2, s[0:1] offset:2048
	global_load_dwordx4 v[44:47], v2, s[0:1] offset:3072
	s_waitcnt vmcnt(0)
	s_branch .Lnbody_2

.Lnbody_2:
	v_mov_b32_e32 v16, v32
	v_mov_b32_e32 v17, v33
	v_mov_b32_e32 v18, v34
	v_mov_b32_e32 v19, v35
	v_mov_b32_e32 v20, v36
	v_mov_b32_e32 v21, v37
	v_mov_b32_e32 v22, v38
	v_mov_b32_e32 v23, v39
	v_mov_b32_e32 v24, v40
	v_mov_b32_e32 v25, v41
	v_mov_b32_e32 v26, v42
	v_mov_b32_e32 v27, v43
	v_mov_b32_e32 v28, v44
	v_mov_b32_e32 v29, v45
	v_mov_b32_e32 v30, v46
	v_mov_b32_e32 v31, v47
	s_lshl_b32 s2, s98, 12
	s_add_u32 s2, s94, s2
	s_addc_u32 s3, s95, 0
	global_store_dwordx4 v2, v[16:19], s[2:3]
	global_store_dwordx4 v2, v[20:23], s[2:3] offset:1024
	global_store_dwordx4 v2, v[24:27], s[2:3] offset:2048
	global_store_dwordx4 v2, v[28:31], s[2:3] offset:3072
	s_min_u32 s0, s98, 0x4000
	s_lshr_b32 s0, s0, 11
	s_mul_i32 s0, s0, 0x6000
	s_add_u32 s2, s100, s0
	s_addc_u32 s3, s101, 0
	global_load_dwordx4 v[80:83], v2, s[2:3]
	global_load_dwordx4 v[84:87], v2, s[2:3] offset:1024
	global_load_dwordx4 v[88:91], v2, s[2:3] offset:2048
	global_load_dwordx4 v[92:95], v2, s[2:3] offset:3072
	s_add_u32 s0, s2, 0x1000
	s_addc_u32 s1, s3, 0
	global_load_dwordx4 v[64:67], v2, s[0:1]
	global_load_dwordx4 v[68:71], v2, s[0:1] offset:1024
	global_load_dwordx4 v[72:75], v2, s[0:1] offset:2048
	global_load_dwordx4 v[76:79], v2, s[0:1] offset:3072
	s_add_u32 s2, s98, s91
	s_cmp_lt_u32 s2, s99
	s_cselect_b32 s3, s2, s98
	s_mov_b32 s99, s3
	s_cmp_lt_u32 s99, 0x4000
	s_cbranch_scc0 .Lnctx_p2
	v_readlane_b32 s0, v252, 18
	v_readlane_b32 s1, v252, 19
	s_lshl_b32 s3, s99, 12
	s_branch .Lnjoin_p2
.Lnctx_p2:
	v_readlane_b32 s0, v252, 22
	v_readlane_b32 s1, v252, 23
	s_sub_u32 s3, s99, 0x4000
	s_lshl_b32 s3, s3, 12
.Lnjoin_p2:
	s_nop 1
	s_add_u32 s0, s0, s3
	s_addc_u32 s1, s1, 0
	s_movk_i32 s99, 0x4800
	global_load_dwordx4 v[32:35], v2, s[0:1]
	global_load_dwordx4 v[36:39], v2, s[0:1] offset:1024
	global_load_dwordx4 v[40:43], v2, s[0:1] offset:2048
	global_load_dwordx4 v[44:47], v2, s[0:1] offset:3072
	v_mul_f32_e32 v97, v16, v16
	v_mul_f32_e32 v98, v20, v20
	v_mul_f32_e32 v99, v24, v24
	v_mul_f32_e32 v100, v28, v28
	v_fmac_f32_e32 v97, v17, v17
	v_fmac_f32_e32 v98, v21, v21
	v_fmac_f32_e32 v99, v25, v25
	v_fmac_f32_e32 v100, v29, v29
	v_fmac_f32_e32 v97, v18, v18
	v_fmac_f32_e32 v98, v22, v22
	v_fmac_f32_e32 v99, v26, v26
	v_fmac_f32_e32 v100, v30, v30
	v_fmac_f32_e32 v97, v19, v19
	v_fmac_f32_e32 v98, v23, v23
	v_fmac_f32_e32 v99, v27, v27
	v_fmac_f32_e32 v100, v31, v31
	v_add_f32_e32 v97, v97, v98
	v_add_f32_e32 v99, v99, v100
	v_add_f32_e32 v96, v97, v99
	ds_bpermute_b32 v97, v4, v96
	s_waitcnt lgkmcnt(0)
	v_add_f32_e32 v96, v96, v97
	ds_bpermute_b32 v97, v5, v96
	s_waitcnt lgkmcnt(0)
	v_add_f32_e32 v96, v96, v97
	ds_bpermute_b32 v97, v6, v96
	s_waitcnt lgkmcnt(0)
	v_add_f32_e32 v96, v96, v97
	ds_bpermute_b32 v97, v7, v96
	s_waitcnt lgkmcnt(0)
	v_add_f32_e32 v96, v96, v97
	ds_bpermute_b32 v97, v8, v96
	s_waitcnt lgkmcnt(0)
	v_add_f32_e32 v96, v96, v97
	ds_bpermute_b32 v97, v9, v96
	s_waitcnt lgkmcnt(0)
	v_add_f32_e32 v96, v96, v97
	v_fmamk_f32 v96, v96, 0x3a800000, v189
	v_rsq_f32_e32 v96, v96
	v_readfirstlane_b32 s0, v110
	v_readfirstlane_b32 s1, v111
	s_lshl_b32 s3, s98, 11
	s_add_u32 s0, s0, s3
	s_addc_u32 s1, s1, 0
	s_waitcnt vmcnt(4)
	v_mul_f32_e32 v16, v16, v96
	v_mul_f32_e32 v17, v17, v96
	v_mul_f32_e32 v18, v18, v96
	v_mul_f32_e32 v19, v19, v96
	v_mul_f32_e32 v20, v20, v96
	v_mul_f32_e32 v21, v21, v96
	v_mul_f32_e32 v22, v22, v96
	v_mul_f32_e32 v23, v23, v96
	v_mul_f32_e32 v24, v24, v96
	v_mul_f32_e32 v25, v25, v96
	v_mul_f32_e32 v26, v26, v96
	v_mul_f32_e32 v27, v27, v96
	v_mul_f32_e32 v28, v28, v96
	v_mul_f32_e32 v29, v29, v96
	v_mul_f32_e32 v30, v30, v96
	v_mul_f32_e32 v31, v31, v96
	v_mul_f32_e32 v16, v16, v48
	v_mul_f32_e32 v17, v17, v49
	v_mul_f32_e32 v18, v18, v50
	v_mul_f32_e32 v19, v19, v51
	v_mul_f32_e32 v20, v20, v52
	v_mul_f32_e32 v21, v21, v53
	v_mul_f32_e32 v22, v22, v54
	v_mul_f32_e32 v23, v23, v55
	v_mul_f32_e32 v24, v24, v56
	v_mul_f32_e32 v25, v25, v57
	v_mul_f32_e32 v26, v26, v58
	v_mul_f32_e32 v27, v27, v59
	v_mul_f32_e32 v28, v28, v60
	v_mul_f32_e32 v29, v29, v61
	v_mul_f32_e32 v30, v30, v62
	v_mul_f32_e32 v31, v31, v63
	v_add_f32_e32 v64, 1.0, v64
	v_add_f32_e32 v65, 1.0, v65
	v_add_f32_e32 v66, 1.0, v66
	v_add_f32_e32 v67, 1.0, v67
	v_add_f32_e32 v68, 1.0, v68
	v_add_f32_e32 v69, 1.0, v69
	v_add_f32_e32 v70, 1.0, v70
	v_add_f32_e32 v71, 1.0, v71
	v_add_f32_e32 v72, 1.0, v72
	v_add_f32_e32 v73, 1.0, v73
	v_add_f32_e32 v74, 1.0, v74
	v_add_f32_e32 v75, 1.0, v75
	v_add_f32_e32 v76, 1.0, v76
	v_add_f32_e32 v77, 1.0, v77
	v_add_f32_e32 v78, 1.0, v78
	v_add_f32_e32 v79, 1.0, v79
	v_fma_f32 v16, v16, v64, v80
	v_fma_f32 v17, v17, v65, v81
	v_fma_f32 v18, v18, v66, v82
	v_fma_f32 v19, v19, v67, v83
	v_fma_f32 v20, v20, v68, v84
	v_fma_f32 v21, v21, v69, v85
	v_fma_f32 v22, v22, v70, v86
	v_fma_f32 v23, v23, v71, v87
	v_fma_f32 v24, v24, v72, v88
	v_fma_f32 v25, v25, v73, v89
	v_fma_f32 v26, v26, v74, v90
	v_fma_f32 v27, v27, v75, v91
	v_fma_f32 v28, v28, v76, v92
	v_fma_f32 v29, v29, v77, v93
	v_fma_f32 v30, v30, v78, v94
	v_fma_f32 v31, v31, v79, v95
	v_cvt_pk_bf16_f32 v102, v16, v17
	v_cvt_pk_bf16_f32 v103, v18, v19
	v_cvt_pk_bf16_f32 v104, v20, v21
	v_cvt_pk_bf16_f32 v105, v22, v23
	v_cvt_pk_bf16_f32 v106, v24, v25
	v_cvt_pk_bf16_f32 v107, v26, v27
	v_cvt_pk_bf16_f32 v108, v28, v29
	v_cvt_pk_bf16_f32 v109, v30, v31
	global_store_dwordx2 v3, v[102:103], s[0:1]
	global_store_dwordx2 v3, v[104:105], s[0:1] offset:512
	global_store_dwordx2 v3, v[106:107], s[0:1] offset:1024
	global_store_dwordx2 v3, v[108:109], s[0:1] offset:1536
	s_mov_b32 s98, s2
	s_cmp_lt_u32 s98, s99
	s_cbranch_scc1 .Lntop_2
	s_branch .LBB0_172

.LBB0_296:
	s_add_i32 s43, s43, s28
	s_cmpk_lg_i32 s28, 0x200
	s_cbranch_scc1 .Lnoremap
	s_cmpk_lt_i32 s43, 0x400
	s_cbranch_scc1 .Lnoremap
	s_addk_i32 s43, 0xff80
	s_cmpk_lt_i32 s43, 0x400
	s_cbranch_scc0 .Lnoremap
	s_mov_b32 s43, 0x7fffffff
.Lnoremap:
	s_cmp_lt_i32 s43, s23
	s_barrier
	s_cbranch_scc0 .LBB0_384

.LBB0_943:
	s_or_b64 exec, exec, s[34:35]
	v_mov_b32_e32 v0, v188
	s_waitcnt lgkmcnt(0)
	s_barrier
	v_readlane_b32 s0, v253, 49
	v_ashrrev_i32_e32 v2, 6, v0
	s_nop 0
	v_add_u32_e32 v18, s0, v2
	v_cmp_gt_i32_e32 vcc, s22, v18
	s_and_saveexec_b64 s[34:35], vcc
	s_movk_i32 s26, 0x6000
	s_mov_b64 s[56:57], 0x4000
	s_cbranch_execz .LBB0_946
	v_readlane_b32 s40, v252, 18
	v_cmp_lt_i32_e32 vcc, v193, v192
	v_readlane_b32 s0, v253, 19
	v_readlane_b32 s48, v252, 26
	v_readlane_b32 s49, v252, 27
	v_readlane_b32 s50, v252, 28
	v_readlane_b32 s51, v252, 29
	v_readlane_b32 s52, v252, 30
	v_readlane_b32 s53, v252, 31
	v_cndmask_b32_e32 v4, v191, v193, vcc
	v_cmp_lt_i32_e32 vcc, v194, v192
	s_lshl_b32 s60, s0, 10
	v_readlane_b32 s54, v252, 32
	v_readlane_b32 s55, v252, 33
	s_mov_b64 s[48:49], s[52:53]
	v_lshlrev_b32_e32 v38, 2, v4
	v_cndmask_b32_e32 v4, v191, v194, vcc
	v_cmp_lt_i32_e32 vcc, v195, v192
	s_lshl_b64 s[0:1], s[60:61], 2
	s_mov_b64 s[50:51], s[54:55]
	v_lshlrev_b32_e32 v39, 2, v4
	v_cndmask_b32_e32 v4, v191, v195, vcc
	v_cmp_lt_i32_e32 vcc, v196, v192
	s_add_u32 s0, s50, s0
	v_and_b32_e32 v3, 63, v0
	v_lshlrev_b32_e32 v40, 2, v4
	v_cndmask_b32_e32 v4, v191, v196, vcc
	v_cmp_lt_i32_e32 vcc, v197, v192
	s_addc_u32 s1, s51, s1
	v_lshlrev_b32_e32 v0, 4, v3
	v_lshlrev_b32_e32 v41, 2, v4
	v_cndmask_b32_e32 v4, v191, v197, vcc
	v_cmp_lt_i32_e32 vcc, v198, v192
	v_lshlrev_b32_e32 v2, 2, v3
	v_lshl_add_u64 v[20:21], s[0:1], 0, v[0:1]
	v_lshlrev_b32_e32 v42, 2, v4
	v_cndmask_b32_e32 v4, v191, v198, vcc
	v_readlane_b32 s0, v253, 40
	v_readlane_b32 s41, v252, 19
	v_readlane_b32 s48, v252, 14
	v_readlane_b32 s50, v251, 2
	v_readlane_b32 s2, v253, 47
	v_lshlrev_b32_e32 v43, 2, v4
	v_or_b32_e32 v4, 0x100, v2
	v_or_b32_e32 v6, 0x200, v2
	v_or_b32_e32 v8, 0x300, v2
	v_lshl_add_u64 v[22:23], s[94:95], 0, v[0:1]
	v_lshlrev_b32_e32 v0, 3, v3
	v_readlane_b32 s1, v253, 41
	s_mov_b32 s27, s25
	v_readlane_b32 s58, v253, 19
	s_mov_b32 s19, 0x800000
	v_readlane_b32 s49, v252, 15
	v_readlane_b32 s51, v251, 3
	v_readlane_b32 s3, v253, 48
	v_lshl_add_u64 v[24:25], s[0:1], 0, v[0:1]
	s_mov_b64 s[40:41], 0
	v_lshlrev_b32_e32 v0, 2, v2
	v_lshlrev_b32_e32 v26, 2, v4
	v_lshlrev_b32_e32 v28, 2, v6
	v_lshlrev_b32_e32 v30, 2, v8
	v_readlane_b32 s42, v252, 20
	v_readlane_b32 s43, v252, 21
	v_readlane_b32 s44, v252, 22
	v_readlane_b32 s45, v252, 23
	v_readlane_b32 s46, v252, 24
	v_readlane_b32 s47, v252, 25
	v_and_b32_e32 v96, 63, v188
	v_lshlrev_b32_e32 v2, 4, v96
	v_lshlrev_b32_e32 v3, 3, v96
	v_lshlrev_b32_e32 v100, 2, v96
	v_xor_b32_e32 v4, 0x80, v100
	v_xor_b32_e32 v5, 0x40, v100
	v_xor_b32_e32 v6, 0x20, v100
	v_xor_b32_e32 v7, 0x10, v100
	v_xor_b32_e32 v8, 0x8, v100
	v_xor_b32_e32 v9, 0x4, v100
	v_readfirstlane_b32 s98, v18
	v_mov_b32_e32 v110, v24
	v_mov_b32_e32 v111, v25
	s_mov_b32 s99, s22
	s_mul_i32 s0, s27, 0x6000
	s_add_u32 s0, s0, 0x3000
	s_add_u32 s100, s2, s0
	s_addc_u32 s101, s3, 0
	v_readfirstlane_b32 s0, v20
	v_readfirstlane_b32 s1, v21
	s_nop 4
	global_load_dwordx4 v[48:51], v2, s[0:1]
	global_load_dwordx4 v[52:55], v2, s[0:1] offset:1024
	global_load_dwordx4 v[56:59], v2, s[0:1] offset:2048
	global_load_dwordx4 v[60:63], v2, s[0:1] offset:3072
	s_lshl_b32 s0, s98, 12
	s_add_u32 s0, s94, s0
	s_addc_u32 s1, s95, 0
	global_load_dwordx4 v[32:35], v2, s[0:1]
	global_load_dwordx4 v[36:39], v2, s[0:1] offset:1024
	global_load_dwordx4 v[40:43], v2, s[0:1] offset:2048
	global_load_dwordx4 v[44:47], v2, s[0:1] offset:3072
	s_waitcnt vmcnt(0)
	s_branch .Lnbody_1
